# MLA loop: PV-A V-fragment LDS reads hoisted above the exponent block; sub/exp in place
# speedup vs baseline: 1.0049x; 1.0049x over previous
.LBB0_748:
	v_lshl_add_u32 v202, s12, 1, v214
	v_add_u32_e32 v203, 0x3000, v202
	v_add_u32_e32 v208, 0x4000, v202
	ds_read2_b64 v[6:9], v203 offset0:128 offset1:130
	ds_read2_b64 v[2:5], v203 offset0:132 offset1:134
	ds_read2_b64 v[10:13], v208 offset0:192 offset1:194
	v_sub_f32_e32 v112, v112, v215
	v_sub_f32_e32 v113, v113, v215
	v_sub_f32_e32 v114, v114, v215
	v_sub_f32_e32 v115, v115, v215
	v_sub_f32_e32 v116, v116, v215
	v_sub_f32_e32 v117, v117, v215
	v_sub_f32_e32 v118, v118, v215
	v_sub_f32_e32 v119, v119, v215
	v_exp_f32_e32 v15, v112
	v_exp_f32_e32 v216, v113
	v_exp_f32_e32 v217, v114
	v_exp_f32_e32 v218, v115
	v_exp_f32_e32 v219, v116
	v_exp_f32_e32 v220, v117
	v_exp_f32_e32 v221, v118
	v_exp_f32_e32 v222, v119
	v_sub_f32_e32 v120, v120, v215
	v_sub_f32_e32 v121, v121, v215
	v_sub_f32_e32 v122, v122, v215
	v_sub_f32_e32 v123, v123, v215
	v_sub_f32_e32 v124, v124, v215
	v_sub_f32_e32 v125, v125, v215
	v_sub_f32_e32 v126, v126, v215
	v_sub_f32_e32 v127, v127, v215
	v_exp_f32_e32 v223, v120
	v_exp_f32_e32 v224, v121
	v_exp_f32_e32 v225, v122
	v_exp_f32_e32 v226, v123
	v_exp_f32_e32 v227, v124
	v_exp_f32_e32 v228, v125
	v_exp_f32_e32 v229, v126
	v_exp_f32_e32 v230, v127
	v_sub_f32_e32 v128, v128, v215
	v_sub_f32_e32 v129, v129, v215
	v_sub_f32_e32 v130, v130, v215
	v_sub_f32_e32 v131, v131, v215
	v_sub_f32_e32 v132, v132, v215
	v_sub_f32_e32 v133, v133, v215
	v_sub_f32_e32 v134, v134, v215
	v_sub_f32_e32 v135, v135, v215
	v_exp_f32_e32 v231, v128
	v_exp_f32_e32 v232, v129
	v_exp_f32_e32 v233, v130
	v_exp_f32_e32 v234, v131
	v_exp_f32_e32 v132, v132
	v_exp_f32_e32 v133, v133
	v_exp_f32_e32 v134, v134
	v_exp_f32_e32 v135, v135
	v_sub_f32_e32 v136, v136, v215
	v_sub_f32_e32 v137, v137, v215
	v_sub_f32_e32 v138, v138, v215
	v_sub_f32_e32 v139, v139, v215
	v_sub_f32_e32 v140, v140, v215
	v_sub_f32_e32 v141, v141, v215
	v_sub_f32_e32 v142, v142, v215
	v_sub_f32_e32 v143, v143, v215
	v_exp_f32_e32 v136, v136
	v_exp_f32_e32 v137, v137
	v_exp_f32_e32 v138, v138
	v_exp_f32_e32 v139, v139
	v_exp_f32_e32 v140, v140
	v_exp_f32_e32 v141, v141
	v_exp_f32_e32 v142, v142
	v_exp_f32_e32 v143, v143
	v_mov_b32_e32 v128, v203
	v_mov_b32_e32 v129, v208
	v_cvt_pk_bf16_f32 v112, v15, v216
	v_cvt_pk_bf16_f32 v113, v217, v218
	v_cvt_pk_bf16_f32 v114, v219, v220
	v_cvt_pk_bf16_f32 v115, v221, v222
	v_cvt_pk_bf16_f32 v116, v223, v224
	v_cvt_pk_bf16_f32 v117, v225, v226
	s_waitcnt lgkmcnt(2)
	v_mfma_f32_32x32x16_bf16 v[64:79], v[6:9], v[112:115], v[64:79]
	v_cvt_pk_bf16_f32 v118, v227, v228
	v_cvt_pk_bf16_f32 v119, v229, v230
	ds_read2_b64 v[120:123], v129 offset0:200 offset1:202
	v_max_f32_e32 v202, v97, v97
	v_max_f32_e32 v203, v96, v96
	v_max_f32_e32 v202, v203, v202
	v_max3_f32 v202, v202, v98, v99
	s_waitcnt lgkmcnt(1)
	v_mfma_f32_32x32x16_bf16 v[48:63], v[10:13], v[112:115], v[48:63]
	ds_read2_b64 v[112:115], v129 offset0:196 offset1:198
	v_max3_f32 v202, v202, v100, v101
	v_max3_f32 v202, v202, v102, v103
	v_max3_f32 v202, v202, v104, v105
	v_max3_f32 v202, v202, v106, v107
	v_cvt_pk_bf16_f32 v124, v231, v232
	v_cvt_pk_bf16_f32 v125, v233, v234
	v_mfma_f32_32x32x16_bf16 v[64:79], v[2:5], v[116:119], v[64:79]
	v_cvt_pk_bf16_f32 v126, v132, v133
	v_cvt_pk_bf16_f32 v127, v134, v135
	v_max3_f32 v202, v202, v108, v109
	v_max3_f32 v202, v202, v110, v111
	v_max3_f32 v202, v202, v80, v81
	v_max3_f32 v202, v202, v82, v83
	v_max3_f32 v202, v202, v84, v85
	s_waitcnt lgkmcnt(0)
	v_mfma_f32_32x32x16_bf16 v[48:63], v[112:115], v[116:119], v[48:63]
	ds_read2_b64 v[116:119], v128 offset0:136 offset1:138
	v_max3_f32 v202, v202, v86, v87
	v_max3_f32 v202, v202, v88, v89
	v_max3_f32 v202, v202, v90, v91
	v_max3_f32 v202, v202, v92, v93
	v_cvt_pk_bf16_f32 v236, v136, v137
	v_cvt_pk_bf16_f32 v237, v138, v139
	s_waitcnt lgkmcnt(0)
	v_mfma_f32_32x32x16_bf16 v[64:79], v[116:119], v[124:127], v[64:79]
	v_cvt_pk_bf16_f32 v238, v140, v141
	v_cvt_pk_bf16_f32 v239, v142, v143
	v_max3_f32 v202, v202, v94, v95
	v_mov_b32_e32 v203, v202
	s_nop 1
	v_permlane32_swap_b32_e32 v202, v203
	v_max_f32_e32 v203, v203, v203
	v_mfma_f32_32x32x16_bf16 v[48:63], v[120:123], v[124:127], v[48:63]
	ds_read2_b64 v[124:127], v128 offset0:140 offset1:142
	ds_read2_b64 v[128:131], v129 offset0:204 offset1:206
	v_max_f32_e32 v208, v202, v203
	v_add_f32_e32 v203, 0xc1000000, v208
	v_cmp_gt_f32_e32 vcc, v203, v14
	s_waitcnt lgkmcnt(1)
	v_mfma_f32_32x32x16_bf16 v[64:79], v[124:127], v[236:239], v[64:79]
	s_waitcnt lgkmcnt(0)
	v_mfma_f32_32x32x16_bf16 v[48:63], v[128:131], v[236:239], v[48:63]
	s_cbranch_vccz .LBB0_750
	v_max_f32_e32 v202, v208, v208
	v_max_f32_e32 v203, v14, v14
	v_max_f32_e32 v202, v203, v202
	v_sub_f32_e32 v14, v14, v202
	v_exp_f32_e32 v14, v14
	s_nop 0
	v_mul_f32_e32 v195, v195, v14
	v_pk_mul_f32 v[46:47], v[46:47], v[14:15] op_sel_hi:[1,0]
	v_pk_mul_f32 v[44:45], v[44:45], v[14:15] op_sel_hi:[1,0]
	v_pk_mul_f32 v[42:43], v[42:43], v[14:15] op_sel_hi:[1,0]
	v_pk_mul_f32 v[40:41], v[40:41], v[14:15] op_sel_hi:[1,0]
	v_pk_mul_f32 v[38:39], v[38:39], v[14:15] op_sel_hi:[1,0]
	v_pk_mul_f32 v[36:37], v[36:37], v[14:15] op_sel_hi:[1,0]
	v_pk_mul_f32 v[34:35], v[34:35], v[14:15] op_sel_hi:[1,0]
	v_pk_mul_f32 v[32:33], v[32:33], v[14:15] op_sel_hi:[1,0]
	v_pk_mul_f32 v[30:31], v[30:31], v[14:15] op_sel_hi:[1,0]
	v_pk_mul_f32 v[28:29], v[28:29], v[14:15] op_sel_hi:[1,0]
	v_pk_mul_f32 v[26:27], v[26:27], v[14:15] op_sel_hi:[1,0]
	v_pk_mul_f32 v[24:25], v[24:25], v[14:15] op_sel_hi:[1,0]
	v_pk_mul_f32 v[22:23], v[22:23], v[14:15] op_sel_hi:[1,0]
	v_pk_mul_f32 v[20:21], v[20:21], v[14:15] op_sel_hi:[1,0]
	v_pk_mul_f32 v[18:19], v[18:19], v[14:15] op_sel_hi:[1,0]
	v_pk_mul_f32 v[16:17], v[16:17], v[14:15] op_sel_hi:[1,0]
	v_mov_b32_e32 v14, v202
